# speedup vs baseline: 1.0026x; 1.0015x over previous
; #define PG8_STAGE(bufoff, gbase, voff) do { _Pragma("unroll") for (int _i = 0; _i < 2; ++_i) \
;         __builtin_amdgcn_global_load_lds((const unsigned*)((const char*)(gbase) + (voff)[_i]), (LAS unsigned*)(lds + (bufoff) + ldsw + _i * 8192), 16, 0, 0); } while (0)
; #define PG8_LDA(dst, b, h) do { _Pragma("unroll") for (int m = 0; m < 4; ++m) _Pragma("unroll") for (int k = 0; k < 2; ++k) dst[m][k] = *(const LAS bf16x8*)(lds + PG8_SA(b, h) + aoff + m * 2048 + k * 1024); } while (0)
; #define PG8_LDB(dst, b, h) do { _Pragma("unroll") for (int n = 0; n < 2; ++n) _Pragma("unroll") for (int k = 0; k < 2; ++k) dst[n][k] = *(const LAS bf16x8*)(lds + PG8_SB(b, h) + boff + n * 2048 + k * 1024); } while (0)
; #define PG8_MMA(ai, bj, At, Bt) do { __builtin_amdgcn_s_setprio(1); _Pragma("unroll") for (int m = 0; m < 4; ++m) _Pragma("unroll") for (int n = 0; n < 2; ++n) _Pragma("unroll") for (int k = 0; k < 2; ++k) \
;         acc[ai][bj][m][n] = __builtin_amdgcn_mfma_f32_16x16x32_bf16(Bt[n][k], At[m][k], acc[ai][bj][m][n], 0, 0, 0); __builtin_amdgcn_s_setprio(0); } while (0)
; #define PG8_WAIT_V(n) asm volatile("s_waitcnt vmcnt(" #n ")" ::: "memory")
; #define PG8_WAIT_L(n) asm volatile("s_waitcnt lgkmcnt(" #n ")" ::: "memory")
; #define PG8_BAR __builtin_amdgcn_s_barrier()
; #define PG8_SCHED __builtin_amdgcn_sched_barrier(0)
; template <class Epi, class Pre, bool AG = false>
; __device__ __forceinline__ void gemm_phase(LAS unsigned char* lds, const Gemm g, const StaticOrder& S, const Epi& E, const Pre& P) {
;     ...
;             PG8_WAIT_V(8); PG8_WAIT_L(0); PG8_BAR; PG8_MMA(0, 0, At, B0); PG8_MMA(0, 1, At, B1); PG8_BAR; PG8_SCHED;
;             PG8_LDA(At, 0, 1); PG8_STAGE(PG8_SB(0, 0), b2, voffB); PG8_STAGE(PG8_SB(0, 1), b2 + hstep, voffB); PG8_STAGE(PG8_SA(0, 0), a2, voffA);
;             PG8_WAIT_V(8); PG8_WAIT_L(0); PG8_BAR; PG8_MMA(1, 0, At, B0); PG8_MMA(1, 1, At, B1); PG8_BAR; PG8_SCHED;
;             PG8_LDB(B0, 1, 0); PG8_LDB(B1, 1, 1); PG8_SCHED; PG8_LDA(At, 1, 0); PG8_STAGE(PG8_SA(0, 1), a2 + hstepA, voffA);
;             PG8_WAIT_V(8); PG8_WAIT_L(0); PG8_BAR; PG8_MMA(0, 0, At, B0); PG8_MMA(0, 1, At, B1); PG8_BAR; PG8_SCHED;
.Lpw_gu_1_done:
	s_waitcnt lgkmcnt(0)
	s_barrier
	s_setprio 1
	v_mfma_f32_16x16x32_bf16 v[58:61], v[140:143], v[174:177], 0
	v_mfma_f32_16x16x32_bf16 v[50:53], v[150:153], v[174:177], 0
	v_mfma_f32_16x16x32_bf16 v[42:45], v[140:143], v[198:201], 0
	v_mfma_f32_16x16x32_bf16 v[34:37], v[150:153], v[198:201], 0
	v_mfma_f32_16x16x32_bf16 v[26:29], v[140:143], v[206:209], 0
	v_mfma_f32_16x16x32_bf16 v[18:21], v[150:153], v[206:209], 0
	v_mfma_f32_16x16x32_bf16 v[10:13], v[140:143], v[214:217], 0
	v_mfma_f32_16x16x32_bf16 v[6:9], v[150:153], v[214:217], 0
	v_mfma_f32_16x16x32_bf16 v[58:61], v[144:147], v[194:197], v[58:61]
	v_mfma_f32_16x16x32_bf16 v[50:53], v[154:157], v[194:197], v[50:53]
	v_mfma_f32_16x16x32_bf16 v[42:45], v[144:147], v[202:205], v[42:45]
	v_mfma_f32_16x16x32_bf16 v[34:37], v[154:157], v[202:205], v[34:37]
	v_mfma_f32_16x16x32_bf16 v[26:29], v[144:147], v[210:213], v[26:29]
	v_mfma_f32_16x16x32_bf16 v[18:21], v[154:157], v[210:213], v[18:21]
	v_mfma_f32_16x16x32_bf16 v[10:13], v[144:147], v[218:221], v[10:13]
	v_mfma_f32_16x16x32_bf16 v[6:9], v[154:157], v[218:221], v[6:9]
	v_mfma_f32_16x16x32_bf16 v[62:65], v[158:161], v[174:177], 0
	v_mfma_f32_16x16x32_bf16 v[54:57], v[166:169], v[174:177], 0
	v_mfma_f32_16x16x32_bf16 v[46:49], v[158:161], v[198:201], 0
	v_mfma_f32_16x16x32_bf16 v[38:41], v[166:169], v[198:201], 0
	v_mfma_f32_16x16x32_bf16 v[30:33], v[158:161], v[206:209], 0
	v_mfma_f32_16x16x32_bf16 v[22:25], v[166:169], v[206:209], 0
	v_mfma_f32_16x16x32_bf16 v[14:17], v[158:161], v[214:217], 0
	v_mfma_f32_16x16x32_bf16 v[2:5], v[166:169], v[214:217], 0
	v_mfma_f32_16x16x32_bf16 v[62:65], v[162:165], v[194:197], v[62:65]
	v_mfma_f32_16x16x32_bf16 v[54:57], v[170:173], v[194:197], v[54:57]
	v_mfma_f32_16x16x32_bf16 v[46:49], v[162:165], v[202:205], v[46:49]
	v_mfma_f32_16x16x32_bf16 v[38:41], v[170:173], v[202:205], v[38:41]
	v_mfma_f32_16x16x32_bf16 v[30:33], v[162:165], v[210:213], v[30:33]
	v_mfma_f32_16x16x32_bf16 v[22:25], v[170:173], v[210:213], v[22:25]
	v_mfma_f32_16x16x32_bf16 v[14:17], v[162:165], v[218:221], v[14:17]
	v_mfma_f32_16x16x32_bf16 v[2:5], v[170:173], v[218:221], v[2:5]
	s_setprio 0
	s_barrier
	s_add_i32 s84, 0, 0x18000
	s_add_i32 s85, 0, 0x1c000
	v_add_u32_e32 v154, s84, v148
	v_add_u32_e32 v170, s85, v148
	ds_read_b128 v[140:143], v154
	ds_read_b128 v[144:147], v154 offset:1024
	ds_read_b128 v[150:153], v154 offset:2048
	ds_read_b128 v[154:157], v154 offset:3072
	ds_read_b128 v[158:161], v170
	ds_read_b128 v[162:165], v170 offset:1024
	ds_read_b128 v[166:169], v170 offset:2048
	ds_read_b128 v[170:173], v170 offset:3072
	s_add_u32 s54, s54, 0x40000
	s_addc_u32 s55, s55, 0
	s_mov_b32 m0, s49
	v_lshl_add_u64 v[190:191], s[54:55], 0, v[136:137]
	ds_read_b128 v[174:177], v149 offset:32768
	ds_read_b128 v[194:197], v149 offset:33792
	ds_read_b128 v[198:201], v149 offset:34816
	ds_read_b128 v[202:205], v149 offset:35840
	ds_read_b128 v[206:209], v149 offset:36864
	ds_read_b128 v[210:213], v149 offset:37888
	ds_read_b128 v[214:217], v149 offset:38912
	ds_read_b128 v[218:221], v149 offset:39936
	global_load_lds_dwordx4 v[190:191], off
	v_lshl_add_u64 v[190:191], s[54:55], 0, v[132:133]
	s_mov_b32 m0, s53
	s_nop 0
	global_load_lds_dwordx4 v[190:191], off
	s_waitcnt vmcnt(8)
	s_waitcnt lgkmcnt(0)
	s_barrier
	s_setprio 1
	v_mfma_f32_16x16x32_bf16 v[122:125], v[140:143], v[174:177], v[122:125]
	v_mfma_f32_16x16x32_bf16 v[114:117], v[150:153], v[174:177], v[114:117]
	v_mfma_f32_16x16x32_bf16 v[106:109], v[140:143], v[198:201], v[106:109]
	v_mfma_f32_16x16x32_bf16 v[98:101], v[150:153], v[198:201], v[98:101]
	v_mfma_f32_16x16x32_bf16 v[90:93], v[140:143], v[206:209], v[90:93]
	v_mfma_f32_16x16x32_bf16 v[82:85], v[150:153], v[206:209], v[82:85]
	v_mfma_f32_16x16x32_bf16 v[74:77], v[140:143], v[214:217], v[74:77]
	v_mfma_f32_16x16x32_bf16 v[66:69], v[150:153], v[214:217], v[66:69]
	v_mfma_f32_16x16x32_bf16 v[122:125], v[144:147], v[194:197], v[122:125]
	v_mfma_f32_16x16x32_bf16 v[114:117], v[154:157], v[194:197], v[114:117]
	v_mfma_f32_16x16x32_bf16 v[106:109], v[144:147], v[202:205], v[106:109]
	v_mfma_f32_16x16x32_bf16 v[98:101], v[154:157], v[202:205], v[98:101]
	v_mfma_f32_16x16x32_bf16 v[90:93], v[144:147], v[210:213], v[90:93]
	v_mfma_f32_16x16x32_bf16 v[82:85], v[154:157], v[210:213], v[82:85]
	v_mfma_f32_16x16x32_bf16 v[74:77], v[144:147], v[218:221], v[74:77]
	v_mfma_f32_16x16x32_bf16 v[66:69], v[154:157], v[218:221], v[66:69]
	v_mfma_f32_16x16x32_bf16 v[126:129], v[158:161], v[174:177], v[126:129]
	v_mfma_f32_16x16x32_bf16 v[118:121], v[166:169], v[174:177], v[118:121]
	v_mfma_f32_16x16x32_bf16 v[110:113], v[158:161], v[198:201], v[110:113]
	v_mfma_f32_16x16x32_bf16 v[102:105], v[166:169], v[198:201], v[102:105]
	v_mfma_f32_16x16x32_bf16 v[94:97], v[158:161], v[206:209], v[94:97]
	v_mfma_f32_16x16x32_bf16 v[86:89], v[166:169], v[206:209], v[86:89]
	v_mfma_f32_16x16x32_bf16 v[78:81], v[158:161], v[214:217], v[78:81]
	v_mfma_f32_16x16x32_bf16 v[70:73], v[166:169], v[214:217], v[70:73]
	v_mfma_f32_16x16x32_bf16 v[126:129], v[162:165], v[194:197], v[126:129]
	v_mfma_f32_16x16x32_bf16 v[118:121], v[170:173], v[194:197], v[118:121]
	v_mfma_f32_16x16x32_bf16 v[110:113], v[162:165], v[202:205], v[110:113]
	v_mfma_f32_16x16x32_bf16 v[102:105], v[170:173], v[202:205], v[102:105]
	v_mfma_f32_16x16x32_bf16 v[94:97], v[162:165], v[210:213], v[94:97]
	v_mfma_f32_16x16x32_bf16 v[86:89], v[170:173], v[210:213], v[86:89]
	v_mfma_f32_16x16x32_bf16 v[78:81], v[162:165], v[218:221], v[78:81]
	v_mfma_f32_16x16x32_bf16 v[70:73], v[170:173], v[218:221], v[70:73]
	s_setprio 0
	s_barrier
; #define PG8_STAGE(bufoff, gbase, voff) do { _Pragma("unroll") for (int _i = 0; _i < 2; ++_i) \
;         __builtin_amdgcn_global_load_lds((const unsigned*)((const char*)(gbase) + (voff)[_i]), (LAS unsigned*)(lds + (bufoff) + ldsw + _i * 8192), 16, 0, 0); } while (0)
; #define PG8_LDA(dst, b, h) do { _Pragma("unroll") for (int m = 0; m < 4; ++m) _Pragma("unroll") for (int k = 0; k < 2; ++k) dst[m][k] = *(const LAS bf16x8*)(lds + PG8_SA(b, h) + aoff + m * 2048 + k * 1024); } while (0)
; #define PG8_MMA(ai, bj, At, Bt) do { __builtin_amdgcn_s_setprio(1); _Pragma("unroll") for (int m = 0; m < 4; ++m) _Pragma("unroll") for (int n = 0; n < 2; ++n) _Pragma("unroll") for (int k = 0; k < 2; ++k) \
;         acc[ai][bj][m][n] = __builtin_amdgcn_mfma_f32_16x16x32_bf16(Bt[n][k], At[m][k], acc[ai][bj][m][n], 0, 0, 0); __builtin_amdgcn_s_setprio(0); } while (0)
; #define PG8_WAIT_V(n) asm volatile("s_waitcnt vmcnt(" #n ")" ::: "memory")
; #define PG8_WAIT_L(n) asm volatile("s_waitcnt lgkmcnt(" #n ")" ::: "memory")
; #define PG8_BAR __builtin_amdgcn_s_barrier()
; #define PG8_SCHED __builtin_amdgcn_sched_barrier(0)
; template <class Epi, class Pre, bool AG = false>
; __device__ __forceinline__ void gemm_phase(LAS unsigned char* lds, const Gemm g, const StaticOrder& S, const Epi& E, const Pre& P) {
;     ...
;             PG8_WAIT_V(8); PG8_WAIT_L(0); PG8_BAR; PG8_MMA(0, 0, At, B0); PG8_MMA(0, 1, At, B1); PG8_BAR; PG8_SCHED;
;             PG8_LDA(At, 1, 1); PG8_STAGE(PG8_SB(1, 0), b3, voffB); PG8_STAGE(PG8_SB(1, 1), b3 + hstep, voffB); PG8_STAGE(PG8_SA(1, 0), a3, voffA);
;             PG8_WAIT_V(8); PG8_WAIT_L(0); PG8_BAR; PG8_MMA(1, 0, At, B0); PG8_MMA(1, 1, At, B1); PG8_BAR; PG8_SCHED;
;         }
	s_add_i32 s54, s84, s31
	v_lshl_add_u64 v[178:179], v[178:179], 0, s[66:67]
	s_mov_b32 m0, s54
	ds_read_b128 v[174:177], v149 offset:49152
	ds_read_b128 v[194:197], v149 offset:50176
	ds_read_b128 v[198:201], v149 offset:51200
	ds_read_b128 v[202:205], v149 offset:52224
	ds_read_b128 v[206:209], v149 offset:53248
	ds_read_b128 v[210:213], v149 offset:54272
	ds_read_b128 v[214:217], v149 offset:55296
	ds_read_b128 v[218:221], v149 offset:56320
	global_load_lds_dwordx4 v[178:179], off
	s_add_i32 m0, s54, 0x2000
	s_add_u32 s46, s46, 0x40080
	v_lshl_add_u64 v[178:179], v[180:181], 0, s[66:67]
	s_addc_u32 s47, s47, 0
	s_add_i32 s54, s85, s31
	global_load_lds_dwordx4 v[178:179], off
	v_lshl_add_u64 v[178:179], s[46:47], 0, v[134:135]
	s_mov_b32 m0, s54
	s_nop 0
	global_load_lds_dwordx4 v[178:179], off
	v_lshl_add_u64 v[178:179], s[46:47], 0, v[130:131]
	s_add_i32 m0, s54, 0x2000
	s_nop 0
	global_load_lds_dwordx4 v[178:179], off
	v_lshl_add_u64 v[178:179], v[182:183], 0, s[66:67]
	s_mov_b32 m0, s58
	s_nop 0
	global_load_lds_dwordx4 v[178:179], off
	v_lshl_add_u64 v[178:179], v[188:189], 0, s[66:67]
	s_mov_b32 m0, s59
	s_nop 0
	global_load_lds_dwordx4 v[178:179], off
	s_waitcnt vmcnt(8)
	s_waitcnt lgkmcnt(0)
	s_barrier
	s_setprio 1
	v_mfma_f32_16x16x32_bf16 v[58:61], v[140:143], v[174:177], v[58:61]
	v_mfma_f32_16x16x32_bf16 v[50:53], v[150:153], v[174:177], v[50:53]
	v_mfma_f32_16x16x32_bf16 v[42:45], v[140:143], v[198:201], v[42:45]
	v_mfma_f32_16x16x32_bf16 v[34:37], v[150:153], v[198:201], v[34:37]
	v_mfma_f32_16x16x32_bf16 v[26:29], v[140:143], v[206:209], v[26:29]
	v_mfma_f32_16x16x32_bf16 v[18:21], v[150:153], v[206:209], v[18:21]
	v_mfma_f32_16x16x32_bf16 v[10:13], v[140:143], v[214:217], v[10:13]
	v_mfma_f32_16x16x32_bf16 v[6:9], v[150:153], v[214:217], v[6:9]
	v_mfma_f32_16x16x32_bf16 v[58:61], v[144:147], v[194:197], v[58:61]
	v_mfma_f32_16x16x32_bf16 v[50:53], v[154:157], v[194:197], v[50:53]
	v_mfma_f32_16x16x32_bf16 v[42:45], v[144:147], v[202:205], v[42:45]
	v_mfma_f32_16x16x32_bf16 v[34:37], v[154:157], v[202:205], v[34:37]
	v_mfma_f32_16x16x32_bf16 v[26:29], v[144:147], v[210:213], v[26:29]
	v_mfma_f32_16x16x32_bf16 v[18:21], v[154:157], v[210:213], v[18:21]
	v_mfma_f32_16x16x32_bf16 v[10:13], v[144:147], v[218:221], v[10:13]
	v_mfma_f32_16x16x32_bf16 v[6:9], v[154:157], v[218:221], v[6:9]
	v_mfma_f32_16x16x32_bf16 v[62:65], v[158:161], v[174:177], v[62:65]
	v_mfma_f32_16x16x32_bf16 v[54:57], v[166:169], v[174:177], v[54:57]
	v_mfma_f32_16x16x32_bf16 v[46:49], v[158:161], v[198:201], v[46:49]
	v_mfma_f32_16x16x32_bf16 v[38:41], v[166:169], v[198:201], v[38:41]
	v_mfma_f32_16x16x32_bf16 v[30:33], v[158:161], v[206:209], v[30:33]
	v_mfma_f32_16x16x32_bf16 v[22:25], v[166:169], v[206:209], v[22:25]
	v_mfma_f32_16x16x32_bf16 v[14:17], v[158:161], v[214:217], v[14:17]
	v_mfma_f32_16x16x32_bf16 v[2:5], v[166:169], v[214:217], v[2:5]
	v_mfma_f32_16x16x32_bf16 v[62:65], v[162:165], v[194:197], v[62:65]
	v_mfma_f32_16x16x32_bf16 v[54:57], v[170:173], v[194:197], v[54:57]
	v_mfma_f32_16x16x32_bf16 v[46:49], v[162:165], v[202:205], v[46:49]
	v_mfma_f32_16x16x32_bf16 v[38:41], v[170:173], v[202:205], v[38:41]
	v_mfma_f32_16x16x32_bf16 v[30:33], v[162:165], v[210:213], v[30:33]
	v_mfma_f32_16x16x32_bf16 v[22:25], v[170:173], v[210:213], v[22:25]
	v_mfma_f32_16x16x32_bf16 v[14:17], v[162:165], v[218:221], v[14:17]
	v_mfma_f32_16x16x32_bf16 v[2:5], v[170:173], v[218:221], v[2:5]
	s_setprio 0
	s_barrier
	s_add_i32 s79, s79, 2
	s_add_u32 s44, s44, 0x100
	s_addc_u32 s45, s45, 0
	s_add_u32 s76, s76, 0x100
	s_addc_u32 s77, s77, 0
	s_cmp_gt_u32 s79, 13
	s_cbranch_scc0 .LBB0_212
	s_branch .Lpeel_gu_after
	.p2align	6

; template <class Epi, class Pre, bool AG = false>
; __device__ __forceinline__ void gemm_phase(LAS unsigned char* lds, const Gemm g, const StaticOrder& S, const Epi& E, const Pre& P) {
;     ...
; #pragma unroll
;         for (int a = 0; a < 2; ++a)
; #pragma unroll
;             for (int b = 0; b < 2; ++b)
; #pragma unroll
;                 for (int m = 0; m < 4; ++m)
; #pragma unroll
;                     for (int n = 0; n < 2; ++n) acc[a][b][m][n] = (f32x4){0.f, 0.f, 0.f, 0.f};
;         cur = nxt; cA = nA; cB = nB; ++ui;
.LBB0_379:
	s_add_u32 s79, s56, 0x100
	v_mov_b32_e32 v2, 0
	s_addc_u32 s84, s57, 0
	s_mov_b32 s85, -2
	s_waitcnt lgkmcnt(0)
	v_mov_b32_e32 v3, v2
	v_mov_b32_e32 v4, v2
	v_mov_b32_e32 v5, v2
	v_mov_b32_e32 v6, v2
	v_mov_b32_e32 v7, v2
	v_mov_b32_e32 v8, v2
	v_mov_b32_e32 v9, v2
	v_mov_b32_e32 v18, v2
	v_mov_b32_e32 v19, v2
	v_mov_b32_e32 v20, v2
	v_mov_b32_e32 v21, v2
	v_mov_b32_e32 v22, v2
	v_mov_b32_e32 v23, v2
	v_mov_b32_e32 v24, v2
	v_mov_b32_e32 v25, v2
	v_mov_b32_e32 v34, v2
	v_mov_b32_e32 v35, v2
	v_mov_b32_e32 v36, v2
	v_mov_b32_e32 v37, v2
	v_mov_b32_e32 v38, v2
	v_mov_b32_e32 v39, v2
	v_mov_b32_e32 v40, v2
	v_mov_b32_e32 v41, v2
	v_mov_b32_e32 v50, v2
	v_mov_b32_e32 v51, v2
	v_mov_b32_e32 v52, v2
	v_mov_b32_e32 v53, v2
	v_mov_b32_e32 v54, v2
	v_mov_b32_e32 v55, v2
	v_mov_b32_e32 v56, v2
	v_mov_b32_e32 v57, v2
	v_mov_b32_e32 v10, v2
	v_mov_b32_e32 v11, v2
	v_mov_b32_e32 v12, v2
	v_mov_b32_e32 v13, v2
	v_mov_b32_e32 v14, v2
	v_mov_b32_e32 v15, v2
	v_mov_b32_e32 v16, v2
	v_mov_b32_e32 v17, v2
	v_mov_b32_e32 v26, v2
	v_mov_b32_e32 v27, v2
	v_mov_b32_e32 v28, v2
	v_mov_b32_e32 v29, v2
	v_mov_b32_e32 v30, v2
	v_mov_b32_e32 v31, v2
	v_mov_b32_e32 v32, v2
	v_mov_b32_e32 v33, v2
	v_mov_b32_e32 v42, v2
	v_mov_b32_e32 v43, v2
	v_mov_b32_e32 v44, v2
	v_mov_b32_e32 v45, v2
	v_mov_b32_e32 v46, v2
	v_mov_b32_e32 v47, v2
	v_mov_b32_e32 v48, v2
	v_mov_b32_e32 v49, v2
	v_mov_b32_e32 v58, v2
	v_mov_b32_e32 v59, v2
	v_mov_b32_e32 v60, v2
	v_mov_b32_e32 v61, v2
	v_mov_b32_e32 v62, v2
	v_mov_b32_e32 v63, v2
	v_mov_b32_e32 v64, v2
	v_mov_b32_e32 v65, v2
	v_mov_b32_e32 v66, v2
	v_mov_b32_e32 v67, v2
	v_mov_b32_e32 v68, v2
	v_mov_b32_e32 v69, v2
	v_mov_b32_e32 v70, v2
	v_mov_b32_e32 v71, v2
	v_mov_b32_e32 v72, v2
	v_mov_b32_e32 v73, v2
	v_mov_b32_e32 v82, v2
	v_mov_b32_e32 v83, v2
	v_mov_b32_e32 v84, v2
	v_mov_b32_e32 v85, v2
	v_mov_b32_e32 v86, v2
	v_mov_b32_e32 v87, v2
	v_mov_b32_e32 v88, v2
	v_mov_b32_e32 v89, v2
	v_mov_b32_e32 v98, v2
	v_mov_b32_e32 v99, v2
	v_mov_b32_e32 v100, v2
	v_mov_b32_e32 v101, v2
	v_mov_b32_e32 v102, v2
	v_mov_b32_e32 v103, v2
	v_mov_b32_e32 v104, v2
	v_mov_b32_e32 v105, v2
	v_mov_b32_e32 v126, v2
	v_mov_b32_e32 v127, v2
	v_mov_b32_e32 v128, v2
	v_mov_b32_e32 v129, v2
	v_mov_b32_e32 v130, v2
	v_mov_b32_e32 v131, v2
	v_mov_b32_e32 v132, v2
	v_mov_b32_e32 v133, v2
	v_mov_b32_e32 v74, v2
	v_mov_b32_e32 v75, v2
	v_mov_b32_e32 v76, v2
	v_mov_b32_e32 v77, v2
	v_mov_b32_e32 v78, v2
	v_mov_b32_e32 v79, v2
	v_mov_b32_e32 v80, v2
	v_mov_b32_e32 v81, v2
	v_mov_b32_e32 v90, v2
	v_mov_b32_e32 v91, v2
	v_mov_b32_e32 v92, v2
	v_mov_b32_e32 v93, v2
	v_mov_b32_e32 v94, v2
	v_mov_b32_e32 v95, v2
	v_mov_b32_e32 v96, v2
	v_mov_b32_e32 v97, v2
	v_mov_b32_e32 v106, v2
	v_mov_b32_e32 v107, v2
	v_mov_b32_e32 v108, v2
	v_mov_b32_e32 v109, v2
	v_mov_b32_e32 v110, v2
	v_mov_b32_e32 v111, v2
	v_mov_b32_e32 v112, v2
	v_mov_b32_e32 v113, v2
	v_mov_b32_e32 v138, v2
	v_mov_b32_e32 v139, v2
	v_mov_b32_e32 v140, v2
	v_mov_b32_e32 v141, v2
	v_mov_b32_e32 v142, v2
	v_mov_b32_e32 v143, v2
	v_mov_b32_e32 v144, v2
	v_mov_b32_e32 v145, v2
	.p2align	6

; template <class Epi, class Pre, bool AG = false>
; __device__ __forceinline__ void gemm_phase(LAS unsigned char* lds, const Gemm g, const StaticOrder& S, const Epi& E, const Pre& P) {
;     ...
;         const bool has_next = S.next(ui + 1, nxt);
;         const char* nA = has_next ? (const char*)g.A + (size_t)nxt.pm * tstepA : cA; const char* nB = has_next ? (const char*)g.Bt + (size_t)nxt.pn * tstep : cB;
;         for (int t = 0; t < nt; t += 2) {
;             const bool last = (t == nt - 2);
;             const char* a1 = cA + (size_t)(t + 1) * kstepA;
;             const char* a2 = last ? nA : cA + (size_t)(t + 2) * kstepA; const char* b2 = last ? nB : cB + (size_t)(t + 2) * kstep;
;             const char* a3 = a2 + kstepA; const char* b3 = b2 + kstep;
;             if constexpr (Epi::MIDK) { if (t == E.midk_t) E.mid(acc, cur, ui, wr, wc, fr, fq); }
;             PG8_LDB(B0, 0, 0); PG8_LDB(B1, 0, 1); PG8_SCHED; PG8_LDA(At, 0, 0); PG8_STAGE(PG8_SA(1, 1), a1 + hstepA, voffA);
;             PG8_WAIT_V(8); PG8_WAIT_L(0); PG8_BAR; PG8_MMA(0, 0, At, B0); PG8_MMA(0, 1, At, B1); PG8_BAR; PG8_SCHED;
;             PG8_LDA(At, 0, 1); PG8_STAGE(PG8_SB(0, 0), b2, voffB); PG8_STAGE(PG8_SB(0, 1), b2 + hstep, voffB); PG8_STAGE(PG8_SA(0, 0), a2, voffA);
;             PG8_WAIT_V(8); PG8_WAIT_L(0); PG8_BAR; PG8_MMA(1, 0, At, B0); PG8_MMA(1, 1, At, B1); PG8_BAR; PG8_SCHED;
;             PG8_LDB(B0, 1, 0); PG8_LDB(B1, 1, 1); PG8_SCHED; PG8_LDA(At, 1, 0); PG8_STAGE(PG8_SA(0, 1), a2 + hstepA, voffA);
;             PG8_WAIT_V(8); PG8_WAIT_L(0); PG8_BAR; PG8_MMA(0, 0, At, B0); PG8_MMA(0, 1, At, B1); PG8_BAR; PG8_SCHED;
;             PG8_LDA(At, 1, 1); PG8_STAGE(PG8_SB(1, 0), b3, voffB); PG8_STAGE(PG8_SB(1, 1), b3 + hstep, voffB); PG8_STAGE(PG8_SA(1, 0), a3, voffA);
;             PG8_WAIT_V(8); PG8_WAIT_L(0); PG8_BAR; PG8_MMA(1, 0, At, B0); PG8_MMA(1, 1, At, B1); PG8_BAR; PG8_SCHED;
;         }
;         if (wr == 0) PG8_BAR;
;         {
;             int te = threadIdx.x; asm volatile("" : "+v"(te));
;             const int le = te & 63;
;             E(acc, cur, ui, wr, wc, le & 15, le >> 4);
;         }
;     ...
;         if constexpr (Epi::DOUBLE_OK) E(acc, cur, ui, wr, wc, fr, fq);
;     ...
;         if (!has_next) break;
; #pragma unroll
;         for (int a = 0; a < 2; ++a)
; #pragma unroll
;             for (int b = 0; b < 2; ++b)
; #pragma unroll
;                 for (int m = 0; m < 4; ++m)
.LBB0_478:
	s_ashr_i32 s71, s70, 31
	s_lshl_b64 s[12:13], s[70:71], 19
	s_add_u32 s78, s0, s12
	s_addc_u32 s79, s1, s13
	s_and_b64 s[12:13], s[8:9], exec
	s_cselect_b32 s12, s79, s11
	s_cselect_b32 s13, s78, s10
	s_ashr_i32 s45, s44, 31
	s_lshl_b64 s[56:57], s[44:45], 19
	s_add_u32 s94, s30, s56
	s_addc_u32 s95, s31, s57
	s_and_b64 s[56:57], s[8:9], exec
	s_cselect_b32 s45, s95, s55
	s_cselect_b32 s71, s94, s54
	s_add_u32 s10, s10, 0x40080
	s_addc_u32 s11, s11, 0
	s_add_u32 s85, s54, 0x100
	v_mov_b32_e32 v2, 0
	s_addc_u32 s86, s55, 0
	s_mov_b32 s87, -2
	s_waitcnt lgkmcnt(0)
	v_mov_b32_e32 v3, v2
	v_mov_b32_e32 v4, v2
	v_mov_b32_e32 v5, v2
	v_mov_b32_e32 v6, v2
	v_mov_b32_e32 v7, v2
	v_mov_b32_e32 v8, v2
	v_mov_b32_e32 v9, v2
	v_mov_b32_e32 v18, v2
	v_mov_b32_e32 v19, v2
	v_mov_b32_e32 v20, v2
	v_mov_b32_e32 v21, v2
	v_mov_b32_e32 v22, v2
	v_mov_b32_e32 v23, v2
	v_mov_b32_e32 v24, v2
	v_mov_b32_e32 v25, v2
	v_mov_b32_e32 v34, v2
	v_mov_b32_e32 v35, v2
	v_mov_b32_e32 v36, v2
	v_mov_b32_e32 v37, v2
	v_mov_b32_e32 v38, v2
	v_mov_b32_e32 v39, v2
	v_mov_b32_e32 v40, v2
	v_mov_b32_e32 v41, v2
	v_mov_b32_e32 v50, v2
	v_mov_b32_e32 v51, v2
	v_mov_b32_e32 v52, v2
	v_mov_b32_e32 v53, v2
	v_mov_b32_e32 v54, v2
	v_mov_b32_e32 v55, v2
	v_mov_b32_e32 v56, v2
	v_mov_b32_e32 v57, v2
	v_mov_b32_e32 v10, v2
	v_mov_b32_e32 v11, v2
	v_mov_b32_e32 v12, v2
	v_mov_b32_e32 v13, v2
	v_mov_b32_e32 v14, v2
	v_mov_b32_e32 v15, v2
	v_mov_b32_e32 v16, v2
	v_mov_b32_e32 v17, v2
	v_mov_b32_e32 v26, v2
	v_mov_b32_e32 v27, v2
	v_mov_b32_e32 v28, v2
	v_mov_b32_e32 v29, v2
	v_mov_b32_e32 v30, v2
	v_mov_b32_e32 v31, v2
	v_mov_b32_e32 v32, v2
	v_mov_b32_e32 v33, v2
	v_mov_b32_e32 v42, v2
	v_mov_b32_e32 v43, v2
	v_mov_b32_e32 v44, v2
	v_mov_b32_e32 v45, v2
	v_mov_b32_e32 v46, v2
	v_mov_b32_e32 v47, v2
	v_mov_b32_e32 v48, v2
	v_mov_b32_e32 v49, v2
	v_mov_b32_e32 v58, v2
	v_mov_b32_e32 v59, v2
	v_mov_b32_e32 v60, v2
	v_mov_b32_e32 v61, v2
	v_mov_b32_e32 v62, v2
	v_mov_b32_e32 v63, v2
	v_mov_b32_e32 v64, v2
	v_mov_b32_e32 v65, v2
	v_mov_b32_e32 v66, v2
	v_mov_b32_e32 v67, v2
	v_mov_b32_e32 v68, v2
	v_mov_b32_e32 v69, v2
	v_mov_b32_e32 v70, v2
	v_mov_b32_e32 v71, v2
	v_mov_b32_e32 v72, v2
	v_mov_b32_e32 v73, v2
	v_mov_b32_e32 v82, v2
	v_mov_b32_e32 v83, v2
	v_mov_b32_e32 v84, v2
	v_mov_b32_e32 v85, v2
	v_mov_b32_e32 v86, v2
	v_mov_b32_e32 v87, v2
	v_mov_b32_e32 v88, v2
	v_mov_b32_e32 v89, v2
	v_mov_b32_e32 v98, v2
	v_mov_b32_e32 v99, v2
	v_mov_b32_e32 v100, v2
	v_mov_b32_e32 v101, v2
	v_mov_b32_e32 v102, v2
	v_mov_b32_e32 v103, v2
	v_mov_b32_e32 v104, v2
	v_mov_b32_e32 v105, v2
	v_mov_b32_e32 v114, v2
	v_mov_b32_e32 v115, v2
	v_mov_b32_e32 v116, v2
	v_mov_b32_e32 v117, v2
	v_mov_b32_e32 v118, v2
	v_mov_b32_e32 v119, v2
	v_mov_b32_e32 v120, v2
	v_mov_b32_e32 v121, v2
	v_mov_b32_e32 v74, v2
	v_mov_b32_e32 v75, v2
	v_mov_b32_e32 v76, v2
	v_mov_b32_e32 v77, v2
	v_mov_b32_e32 v78, v2
	v_mov_b32_e32 v79, v2
	v_mov_b32_e32 v80, v2
	v_mov_b32_e32 v81, v2
	v_mov_b32_e32 v90, v2
	v_mov_b32_e32 v91, v2
	v_mov_b32_e32 v92, v2
	v_mov_b32_e32 v93, v2
	v_mov_b32_e32 v94, v2
	v_mov_b32_e32 v95, v2
	v_mov_b32_e32 v96, v2
	v_mov_b32_e32 v97, v2
	v_mov_b32_e32 v106, v2
	v_mov_b32_e32 v107, v2
	v_mov_b32_e32 v108, v2
	v_mov_b32_e32 v109, v2
	v_mov_b32_e32 v110, v2
	v_mov_b32_e32 v111, v2
	v_mov_b32_e32 v112, v2
	v_mov_b32_e32 v113, v2
	v_mov_b32_e32 v122, v2
	v_mov_b32_e32 v123, v2
	v_mov_b32_e32 v124, v2
	v_mov_b32_e32 v125, v2
	v_mov_b32_e32 v126, v2
	v_mov_b32_e32 v127, v2
	v_mov_b32_e32 v128, v2
	v_mov_b32_e32 v129, v2
	.p2align	6

; template <class Epi, class Pre, bool AG = false>
; __device__ __forceinline__ void gemm_phase(LAS unsigned char* lds, const Gemm g, const StaticOrder& S, const Epi& E, const Pre& P) {
;     ...
;         const bool has_next = S.next(ui + 1, nxt);
;         const char* nA = has_next ? (const char*)g.A + (size_t)nxt.pm * tstepA : cA; const char* nB = has_next ? (const char*)g.Bt + (size_t)nxt.pn * tstep : cB;
;         for (int t = 0; t < nt; t += 2) {
;             const bool last = (t == nt - 2);
;             const char* a1 = cA + (size_t)(t + 1) * kstepA;
;             const char* a2 = last ? nA : cA + (size_t)(t + 2) * kstepA; const char* b2 = last ? nB : cB + (size_t)(t + 2) * kstep;
;             const char* a3 = a2 + kstepA; const char* b3 = b2 + kstep;
;             if constexpr (Epi::MIDK) { if (t == E.midk_t) E.mid(acc, cur, ui, wr, wc, fr, fq); }
;             PG8_LDB(B0, 0, 0); PG8_LDB(B1, 0, 1); PG8_SCHED; PG8_LDA(At, 0, 0); PG8_STAGE(PG8_SA(1, 1), a1 + hstepA, voffA);
;             PG8_WAIT_V(8); PG8_WAIT_L(0); PG8_BAR; PG8_MMA(0, 0, At, B0); PG8_MMA(0, 1, At, B1); PG8_BAR; PG8_SCHED;
;             PG8_LDA(At, 0, 1); PG8_STAGE(PG8_SB(0, 0), b2, voffB); PG8_STAGE(PG8_SB(0, 1), b2 + hstep, voffB); PG8_STAGE(PG8_SA(0, 0), a2, voffA);
;             PG8_WAIT_V(8); PG8_WAIT_L(0); PG8_BAR; PG8_MMA(1, 0, At, B0); PG8_MMA(1, 1, At, B1); PG8_BAR; PG8_SCHED;
;             PG8_LDB(B0, 1, 0); PG8_LDB(B1, 1, 1); PG8_SCHED; PG8_LDA(At, 1, 0); PG8_STAGE(PG8_SA(0, 1), a2 + hstepA, voffA);
;             PG8_WAIT_V(8); PG8_WAIT_L(0); PG8_BAR; PG8_MMA(0, 0, At, B0); PG8_MMA(0, 1, At, B1); PG8_BAR; PG8_SCHED;
;             PG8_LDA(At, 1, 1); PG8_STAGE(PG8_SB(1, 0), b3, voffB); PG8_STAGE(PG8_SB(1, 1), b3 + hstep, voffB); PG8_STAGE(PG8_SA(1, 0), a3, voffA);
;             PG8_WAIT_V(8); PG8_WAIT_L(0); PG8_BAR; PG8_MMA(1, 0, At, B0); PG8_MMA(1, 1, At, B1); PG8_BAR; PG8_SCHED;
;         }
;         if (wr == 0) PG8_BAR;
;         {
;             int te = threadIdx.x; asm volatile("" : "+v"(te));
;             const int le = te & 63;
;             E(acc, cur, ui, wr, wc, le & 15, le >> 4);
;         }
;     ...
;         if constexpr (Epi::DOUBLE_OK) E(acc, cur, ui, wr, wc, fr, fq);
;     ...
;         if (!has_next) break;
; #pragma unroll
;         for (int a = 0; a < 2; ++a)
; #pragma unroll
;             for (int b = 0; b < 2; ++b)
; #pragma unroll
;                 for (int m = 0; m < 4; ++m)
.LBB0_578:
	s_ashr_i32 s29, s28, 31
	s_lshl_b64 s[12:13], s[28:29], 19
	s_add_u32 s42, s20, s12
	s_addc_u32 s43, s24, s13
	s_and_b64 s[12:13], s[8:9], exec
	s_cselect_b32 s12, s43, s47
	s_cselect_b32 s13, s42, s46
	s_ashr_i32 s27, s26, 31
	s_lshl_b64 s[44:45], s[26:27], 19
	s_add_u32 s44, s25, s44
	s_addc_u32 s45, s30, s45
	s_and_b64 s[56:57], s[8:9], exec
	s_cselect_b32 s27, s45, s55
	s_cselect_b32 s29, s44, s54
	s_add_u32 s46, s46, 0x40080
	s_addc_u32 s47, s47, 0
	s_add_u32 s78, s54, 0x100
	v_mov_b32_e32 v2, 0
	s_addc_u32 s79, s55, 0
	s_mov_b32 s84, -2
	v_mov_b32_e32 v3, v2
	v_mov_b32_e32 v4, v2
	v_mov_b32_e32 v5, v2
	v_mov_b32_e32 v6, v2
	v_mov_b32_e32 v7, v2
	v_mov_b32_e32 v8, v2
	v_mov_b32_e32 v9, v2
	v_mov_b32_e32 v14, v2
	v_mov_b32_e32 v15, v2
	v_mov_b32_e32 v16, v2
	v_mov_b32_e32 v17, v2
	v_mov_b32_e32 v22, v2
	v_mov_b32_e32 v23, v2
	v_mov_b32_e32 v24, v2
	v_mov_b32_e32 v25, v2
	v_mov_b32_e32 v30, v2
	v_mov_b32_e32 v31, v2
	v_mov_b32_e32 v32, v2
	v_mov_b32_e32 v33, v2
	v_mov_b32_e32 v38, v2
	v_mov_b32_e32 v39, v2
	v_mov_b32_e32 v40, v2
	v_mov_b32_e32 v41, v2
	v_mov_b32_e32 v46, v2
	v_mov_b32_e32 v47, v2
	v_mov_b32_e32 v48, v2
	v_mov_b32_e32 v49, v2
	v_mov_b32_e32 v54, v2
	v_mov_b32_e32 v55, v2
	v_mov_b32_e32 v56, v2
	v_mov_b32_e32 v57, v2
	v_mov_b32_e32 v10, v2
	v_mov_b32_e32 v11, v2
	v_mov_b32_e32 v12, v2
	v_mov_b32_e32 v13, v2
	v_mov_b32_e32 v18, v2
	v_mov_b32_e32 v19, v2
	v_mov_b32_e32 v20, v2
	v_mov_b32_e32 v21, v2
	v_mov_b32_e32 v26, v2
	v_mov_b32_e32 v27, v2
	v_mov_b32_e32 v28, v2
	v_mov_b32_e32 v29, v2
	v_mov_b32_e32 v34, v2
	v_mov_b32_e32 v35, v2
	v_mov_b32_e32 v36, v2
	v_mov_b32_e32 v37, v2
	v_mov_b32_e32 v42, v2
	v_mov_b32_e32 v43, v2
	v_mov_b32_e32 v44, v2
	v_mov_b32_e32 v45, v2
	v_mov_b32_e32 v50, v2
	v_mov_b32_e32 v51, v2
	v_mov_b32_e32 v52, v2
	v_mov_b32_e32 v53, v2
	v_mov_b32_e32 v58, v2
	v_mov_b32_e32 v59, v2
	v_mov_b32_e32 v60, v2
	v_mov_b32_e32 v61, v2
	v_mov_b32_e32 v62, v2
	v_mov_b32_e32 v63, v2
	v_mov_b32_e32 v64, v2
	v_mov_b32_e32 v65, v2
	v_mov_b32_e32 v66, v2
	v_mov_b32_e32 v67, v2
	v_mov_b32_e32 v68, v2
	v_mov_b32_e32 v69, v2
	v_mov_b32_e32 v70, v2
	v_mov_b32_e32 v71, v2
	v_mov_b32_e32 v72, v2
	v_mov_b32_e32 v73, v2
	v_mov_b32_e32 v82, v2
	v_mov_b32_e32 v83, v2
	v_mov_b32_e32 v84, v2
	v_mov_b32_e32 v85, v2
	v_mov_b32_e32 v86, v2
	v_mov_b32_e32 v87, v2
	v_mov_b32_e32 v88, v2
	v_mov_b32_e32 v89, v2
	v_mov_b32_e32 v98, v2
	v_mov_b32_e32 v99, v2
	v_mov_b32_e32 v100, v2
	v_mov_b32_e32 v101, v2
	v_mov_b32_e32 v102, v2
	v_mov_b32_e32 v103, v2
	v_mov_b32_e32 v104, v2
	v_mov_b32_e32 v105, v2
	v_mov_b32_e32 v114, v2
	v_mov_b32_e32 v115, v2
	v_mov_b32_e32 v116, v2
	v_mov_b32_e32 v117, v2
	v_mov_b32_e32 v118, v2
	v_mov_b32_e32 v119, v2
	v_mov_b32_e32 v120, v2
	v_mov_b32_e32 v121, v2
	v_mov_b32_e32 v74, v2
	v_mov_b32_e32 v75, v2
	v_mov_b32_e32 v76, v2
	v_mov_b32_e32 v77, v2
	v_mov_b32_e32 v78, v2
	v_mov_b32_e32 v79, v2
	v_mov_b32_e32 v80, v2
	v_mov_b32_e32 v81, v2
	v_mov_b32_e32 v90, v2
	v_mov_b32_e32 v91, v2
	v_mov_b32_e32 v92, v2
	v_mov_b32_e32 v93, v2
	v_mov_b32_e32 v94, v2
	v_mov_b32_e32 v95, v2
	v_mov_b32_e32 v96, v2
	v_mov_b32_e32 v97, v2
	v_mov_b32_e32 v106, v2
	v_mov_b32_e32 v107, v2
	v_mov_b32_e32 v108, v2
	v_mov_b32_e32 v109, v2
	v_mov_b32_e32 v110, v2
	v_mov_b32_e32 v111, v2
	v_mov_b32_e32 v112, v2
	v_mov_b32_e32 v113, v2
	v_mov_b32_e32 v122, v2
	v_mov_b32_e32 v123, v2
	v_mov_b32_e32 v124, v2
	v_mov_b32_e32 v125, v2
	v_mov_b32_e32 v126, v2
	v_mov_b32_e32 v127, v2
	v_mov_b32_e32 v128, v2
	v_mov_b32_e32 v129, v2
	.p2align	6

; template <class Epi, class Pre, bool AG = false>
; __device__ __forceinline__ void gemm_phase(LAS unsigned char* lds, const Gemm g, const StaticOrder& S, const Epi& E, const Pre& P) {
;     ...
;         const bool has_next = S.next(ui + 1, nxt);
;         const char* nA = has_next ? (const char*)g.A + (size_t)nxt.pm * tstepA : cA; const char* nB = has_next ? (const char*)g.Bt + (size_t)nxt.pn * tstep : cB;
;         for (int t = 0; t < nt; t += 2) {
;             const bool last = (t == nt - 2);
;             const char* a1 = cA + (size_t)(t + 1) * kstepA;
;             const char* a2 = last ? nA : cA + (size_t)(t + 2) * kstepA; const char* b2 = last ? nB : cB + (size_t)(t + 2) * kstep;
;             const char* a3 = a2 + kstepA; const char* b3 = b2 + kstep;
;             if constexpr (Epi::MIDK) { if (t == E.midk_t) E.mid(acc, cur, ui, wr, wc, fr, fq); }
;             PG8_LDB(B0, 0, 0); PG8_LDB(B1, 0, 1); PG8_SCHED; PG8_LDA(At, 0, 0); PG8_STAGE(PG8_SA(1, 1), a1 + hstepA, voffA);
;             PG8_WAIT_V(8); PG8_WAIT_L(0); PG8_BAR; PG8_MMA(0, 0, At, B0); PG8_MMA(0, 1, At, B1); PG8_BAR; PG8_SCHED;
;             PG8_LDA(At, 0, 1); PG8_STAGE(PG8_SB(0, 0), b2, voffB); PG8_STAGE(PG8_SB(0, 1), b2 + hstep, voffB); PG8_STAGE(PG8_SA(0, 0), a2, voffA);
;             PG8_WAIT_V(8); PG8_WAIT_L(0); PG8_BAR; PG8_MMA(1, 0, At, B0); PG8_MMA(1, 1, At, B1); PG8_BAR; PG8_SCHED;
;             PG8_LDB(B0, 1, 0); PG8_LDB(B1, 1, 1); PG8_SCHED; PG8_LDA(At, 1, 0); PG8_STAGE(PG8_SA(0, 1), a2 + hstepA, voffA);
;             PG8_WAIT_V(8); PG8_WAIT_L(0); PG8_BAR; PG8_MMA(0, 0, At, B0); PG8_MMA(0, 1, At, B1); PG8_BAR; PG8_SCHED;
;             PG8_LDA(At, 1, 1); PG8_STAGE(PG8_SB(1, 0), b3, voffB); PG8_STAGE(PG8_SB(1, 1), b3 + hstep, voffB); PG8_STAGE(PG8_SA(1, 0), a3, voffA);
;             PG8_WAIT_V(8); PG8_WAIT_L(0); PG8_BAR; PG8_MMA(1, 0, At, B0); PG8_MMA(1, 1, At, B1); PG8_BAR; PG8_SCHED;
;         }
;         if (wr == 0) PG8_BAR;
;         {
;             int te = threadIdx.x; asm volatile("" : "+v"(te));
;             const int le = te & 63;
;             E(acc, cur, ui, wr, wc, le & 15, le >> 4);
;         }
;     ...
;         if constexpr (Epi::DOUBLE_OK) E(acc, cur, ui, wr, wc, fr, fq);
;     ...
;         if (!has_next) break;
; #pragma unroll
;         for (int a = 0; a < 2; ++a)
; #pragma unroll
;             for (int b = 0; b < 2; ++b)
; #pragma unroll
;                 for (int m = 0; m < 4; ++m)
.LBB0_740:
	s_ashr_i32 s29, s28, 31
	s_lshl_b64 s[12:13], s[28:29], 13
	s_add_u32 s42, s0, s12
	s_addc_u32 s43, s1, s13
	s_and_b64 s[12:13], s[8:9], exec
	s_cselect_b32 s12, s43, s11
	s_cselect_b32 s13, s42, s10
	s_ashr_i32 s27, s26, 31
	s_lshl_b64 s[44:45], s[26:27], 18
	s_add_u32 s44, s30, s44
	s_addc_u32 s45, s31, s45
	s_and_b64 s[56:57], s[8:9], exec
	s_cselect_b32 s27, s45, s55
	s_cselect_b32 s29, s44, s54
	s_add_u32 vcc_lo, s54, 0x100
	v_mov_b32_e32 v2, 0
	s_addc_u32 vcc_hi, s55, 0
	s_mov_b32 s87, -2
	v_mov_b32_e32 v3, v2
	v_mov_b32_e32 v4, v2
	v_mov_b32_e32 v5, v2
	v_mov_b32_e32 v6, v2
	v_mov_b32_e32 v7, v2
	v_mov_b32_e32 v8, v2
	v_mov_b32_e32 v9, v2
	v_mov_b32_e32 v18, v2
	v_mov_b32_e32 v19, v2
	v_mov_b32_e32 v20, v2
	v_mov_b32_e32 v21, v2
	v_mov_b32_e32 v22, v2
	v_mov_b32_e32 v23, v2
	v_mov_b32_e32 v24, v2
	v_mov_b32_e32 v25, v2
	v_mov_b32_e32 v34, v2
	v_mov_b32_e32 v35, v2
	v_mov_b32_e32 v36, v2
	v_mov_b32_e32 v37, v2
	v_mov_b32_e32 v38, v2
	v_mov_b32_e32 v39, v2
	v_mov_b32_e32 v40, v2
	v_mov_b32_e32 v41, v2
	v_mov_b32_e32 v50, v2
	v_mov_b32_e32 v51, v2
	v_mov_b32_e32 v52, v2
	v_mov_b32_e32 v53, v2
	v_mov_b32_e32 v54, v2
	v_mov_b32_e32 v55, v2
	v_mov_b32_e32 v56, v2
	v_mov_b32_e32 v57, v2
	v_mov_b32_e32 v10, v2
	v_mov_b32_e32 v11, v2
	v_mov_b32_e32 v12, v2
	v_mov_b32_e32 v13, v2
	v_mov_b32_e32 v14, v2
	v_mov_b32_e32 v15, v2
	v_mov_b32_e32 v16, v2
	v_mov_b32_e32 v17, v2
	v_mov_b32_e32 v26, v2
	v_mov_b32_e32 v27, v2
	v_mov_b32_e32 v28, v2
	v_mov_b32_e32 v29, v2
	v_mov_b32_e32 v30, v2
	v_mov_b32_e32 v31, v2
	v_mov_b32_e32 v32, v2
	v_mov_b32_e32 v33, v2
	v_mov_b32_e32 v42, v2
	v_mov_b32_e32 v43, v2
	v_mov_b32_e32 v44, v2
	v_mov_b32_e32 v45, v2
	v_mov_b32_e32 v46, v2
	v_mov_b32_e32 v47, v2
	v_mov_b32_e32 v48, v2
	v_mov_b32_e32 v49, v2
	v_mov_b32_e32 v66, v2
	v_mov_b32_e32 v67, v2
	v_mov_b32_e32 v68, v2
	v_mov_b32_e32 v69, v2
	v_mov_b32_e32 v70, v2
	v_mov_b32_e32 v71, v2
	v_mov_b32_e32 v72, v2
	v_mov_b32_e32 v73, v2
	v_mov_b32_e32 v82, v2
	v_mov_b32_e32 v83, v2
	v_mov_b32_e32 v84, v2
	v_mov_b32_e32 v85, v2
	v_mov_b32_e32 v86, v2
	v_mov_b32_e32 v87, v2
	v_mov_b32_e32 v88, v2
	v_mov_b32_e32 v89, v2
	v_mov_b32_e32 v98, v2
	v_mov_b32_e32 v99, v2
	v_mov_b32_e32 v100, v2
	v_mov_b32_e32 v101, v2
	v_mov_b32_e32 v102, v2
	v_mov_b32_e32 v103, v2
	v_mov_b32_e32 v104, v2
	v_mov_b32_e32 v105, v2
	v_mov_b32_e32 v114, v2
	v_mov_b32_e32 v115, v2
	v_mov_b32_e32 v116, v2
	v_mov_b32_e32 v117, v2
	v_mov_b32_e32 v118, v2
	v_mov_b32_e32 v119, v2
	v_mov_b32_e32 v120, v2
	v_mov_b32_e32 v121, v2
	v_mov_b32_e32 v130, v2
	v_mov_b32_e32 v131, v2
	v_mov_b32_e32 v132, v2
	v_mov_b32_e32 v133, v2
	v_mov_b32_e32 v134, v2
	v_mov_b32_e32 v135, v2
	v_mov_b32_e32 v136, v2
	v_mov_b32_e32 v137, v2
	v_mov_b32_e32 v90, v2
	v_mov_b32_e32 v91, v2
	v_mov_b32_e32 v92, v2
	v_mov_b32_e32 v93, v2
	v_mov_b32_e32 v94, v2
	v_mov_b32_e32 v95, v2
	v_mov_b32_e32 v96, v2
	v_mov_b32_e32 v97, v2
	v_mov_b32_e32 v106, v2
	v_mov_b32_e32 v107, v2
	v_mov_b32_e32 v108, v2
	v_mov_b32_e32 v109, v2
	v_mov_b32_e32 v110, v2
	v_mov_b32_e32 v111, v2
	v_mov_b32_e32 v112, v2
	v_mov_b32_e32 v113, v2
	v_mov_b32_e32 v122, v2
	v_mov_b32_e32 v123, v2
	v_mov_b32_e32 v124, v2
	v_mov_b32_e32 v125, v2
	v_mov_b32_e32 v126, v2
	v_mov_b32_e32 v127, v2
	v_mov_b32_e32 v128, v2
	v_mov_b32_e32 v129, v2
	v_mov_b32_e32 v158, v2
	v_mov_b32_e32 v159, v2
	v_mov_b32_e32 v160, v2
	v_mov_b32_e32 v161, v2
	v_mov_b32_e32 v162, v2
	v_mov_b32_e32 v163, v2
	v_mov_b32_e32 v164, v2
	v_mov_b32_e32 v165, v2
	.p2align	6

; __device__ __forceinline__ unsigned pk2(float lo, float hi) { unsigned r; asm("v_cvt_pk_bf16_f32 %0, %1, %2" : "=v"(r) : "v"(lo), "v"(hi)); return r; }
; __device__ __forceinline__ void st16_wt(void* p, u32x4 v) { asm volatile("global_store_dwordx4 %0, %1, off sc1\n\ts_nop 1" :: "v"(p), "v"(v) : "memory"); }
; __device__ __forceinline__ void convert_layer(LAS unsigned char* lds, int l, int part, int nparts, int widx, int nworkers, int tid_in) {
;     ...
;         const float* p = a.in[I_P] + (size_t)l * M * PLE; u16* pb = (u16*)(ws + WS_PB) + (size_t)l * M * PLE;
;         const size_t n8l = (size_t)M * PLE / 8, lo = n8l * part / nparts, n8 = n8l * (part + 1) / nparts, stride = (size_t)nworkers * NTHR;
;         for (size_t i = lo + (size_t)widx * NTHR + tid; i < n8; i += 4 * stride) {
;             f32x4 v0[4], v1[4];
; #pragma unroll
;             for (int q = 0; q < 4; ++q) { const size_t ii = i + q * stride; if (ii < n8) { v0[q] = __builtin_nontemporal_load((const f32x4*)(p + ii * 8)); v1[q] = __builtin_nontemporal_load((const f32x4*)(p + ii * 8 + 4)); } }
; #pragma unroll
;             for (int q = 0; q < 4; ++q) { const size_t ii = i + q * stride; if (ii < n8) {
;                 u32x4 w; w.x = pk2(v0[q].x, v0[q].y); w.y = pk2(v0[q].z, v0[q].w); w.z = pk2(v1[q].x, v1[q].y); w.w = pk2(v1[q].z, v1[q].w);
;                 st16_wt(pb + ii * 8, w); } }
;         }
.LBB0_774:
	s_add_u32 s26, s26, s20
	s_addc_u32 s27, s27, s79
	s_mov_b64 s[8:9], 0
	.p2align	6

; template <class Epi, class Pre, bool AG = false>
; __device__ __forceinline__ void gemm_phase(LAS unsigned char* lds, const Gemm g, const StaticOrder& S, const Epi& E, const Pre& P) {
;     ...
;         const bool has_next = S.next(ui + 1, nxt);
;         const char* nA = has_next ? (const char*)g.A + (size_t)nxt.pm * tstepA : cA; const char* nB = has_next ? (const char*)g.Bt + (size_t)nxt.pn * tstep : cB;
;         for (int t = 0; t < nt; t += 2) {
;             const bool last = (t == nt - 2);
;             const char* a1 = cA + (size_t)(t + 1) * kstepA;
;             const char* a2 = last ? nA : cA + (size_t)(t + 2) * kstepA; const char* b2 = last ? nB : cB + (size_t)(t + 2) * kstep;
;             const char* a3 = a2 + kstepA; const char* b3 = b2 + kstep;
;             if constexpr (Epi::MIDK) { if (t == E.midk_t) E.mid(acc, cur, ui, wr, wc, fr, fq); }
;             PG8_LDB(B0, 0, 0); PG8_LDB(B1, 0, 1); PG8_SCHED; PG8_LDA(At, 0, 0); PG8_STAGE(PG8_SA(1, 1), a1 + hstepA, voffA);
;             PG8_WAIT_V(8); PG8_WAIT_L(0); PG8_BAR; PG8_MMA(0, 0, At, B0); PG8_MMA(0, 1, At, B1); PG8_BAR; PG8_SCHED;
;             PG8_LDA(At, 0, 1); PG8_STAGE(PG8_SB(0, 0), b2, voffB); PG8_STAGE(PG8_SB(0, 1), b2 + hstep, voffB); PG8_STAGE(PG8_SA(0, 0), a2, voffA);
;             PG8_WAIT_V(8); PG8_WAIT_L(0); PG8_BAR; PG8_MMA(1, 0, At, B0); PG8_MMA(1, 1, At, B1); PG8_BAR; PG8_SCHED;
;             PG8_LDB(B0, 1, 0); PG8_LDB(B1, 1, 1); PG8_SCHED; PG8_LDA(At, 1, 0); PG8_STAGE(PG8_SA(0, 1), a2 + hstepA, voffA);
;             PG8_WAIT_V(8); PG8_WAIT_L(0); PG8_BAR; PG8_MMA(0, 0, At, B0); PG8_MMA(0, 1, At, B1); PG8_BAR; PG8_SCHED;
;             PG8_LDA(At, 1, 1); PG8_STAGE(PG8_SB(1, 0), b3, voffB); PG8_STAGE(PG8_SB(1, 1), b3 + hstep, voffB); PG8_STAGE(PG8_SA(1, 0), a3, voffA);
;             PG8_WAIT_V(8); PG8_WAIT_L(0); PG8_BAR; PG8_MMA(1, 0, At, B0); PG8_MMA(1, 1, At, B1); PG8_BAR; PG8_SCHED;
;         }
;         if (wr == 0) PG8_BAR;
;         {
;             int te = threadIdx.x; asm volatile("" : "+v"(te));
;             const int le = te & 63;
;             E(acc, cur, ui, wr, wc, le & 15, le >> 4);
;         }
;     ...
;         if constexpr (Epi::DOUBLE_OK) E(acc, cur, ui, wr, wc, fr, fq);
;     ...
;         if (!has_next) break;
; #pragma unroll
;         for (int a = 0; a < 2; ++a)
; #pragma unroll
;             for (int b = 0; b < 2; ++b)
; #pragma unroll
;                 for (int m = 0; m < 4; ++m)
.LBB0_862:
	s_ashr_i32 s43, s42, 31
	s_lshl_b64 s[12:13], s[42:43], 19
	s_add_u32 s44, s20, s12
	s_addc_u32 s45, s24, s13
	s_and_b64 s[12:13], s[6:7], exec
	s_cselect_b32 s12, s45, s9
	s_cselect_b32 s13, s44, s8
	s_ashr_i32 s29, s28, 31
	s_lshl_b64 s[46:47], s[28:29], 19
	s_add_u32 s46, s25, s46
	s_addc_u32 s47, s30, s47
	s_and_b64 s[58:59], s[6:7], exec
	s_cselect_b32 s29, s47, s55
	s_cselect_b32 s43, s46, s54
	s_lshl_b32 s14, s56, 10
	s_add_u32 s56, s8, 0x40080
	s_addc_u32 s57, s9, 0
	s_waitcnt lgkmcnt(0)
	v_mov_b32_e32 v2, v1
	v_mov_b32_e32 v3, v1
	s_add_u32 s79, s54, 0x100
	v_mov_b32_e32 v0, v1
	v_mov_b64_e32 v[6:7], v[2:3]
	v_mov_b64_e32 v[10:11], v[2:3]
	v_mov_b64_e32 v[22:23], v[2:3]
	v_mov_b64_e32 v[26:27], v[2:3]
	v_mov_b64_e32 v[38:39], v[2:3]
	v_mov_b64_e32 v[42:43], v[2:3]
	v_mov_b64_e32 v[54:55], v[2:3]
	v_mov_b64_e32 v[58:59], v[2:3]
	v_mov_b64_e32 v[14:15], v[2:3]
	v_mov_b64_e32 v[18:19], v[2:3]
	v_mov_b64_e32 v[30:31], v[2:3]
	v_mov_b64_e32 v[34:35], v[2:3]
	v_mov_b64_e32 v[46:47], v[2:3]
	v_mov_b64_e32 v[50:51], v[2:3]
	v_mov_b64_e32 v[62:63], v[2:3]
	v_mov_b64_e32 v[66:67], v[2:3]
	v_mov_b64_e32 v[70:71], v[2:3]
	v_mov_b64_e32 v[74:75], v[2:3]
	v_mov_b64_e32 v[86:87], v[2:3]
	v_mov_b64_e32 v[90:91], v[2:3]
	v_mov_b64_e32 v[102:103], v[2:3]
	v_mov_b64_e32 v[106:107], v[2:3]
	v_mov_b64_e32 v[134:135], v[2:3]
	v_mov_b64_e32 v[138:139], v[2:3]
	v_mov_b64_e32 v[78:79], v[2:3]
	v_mov_b64_e32 v[82:83], v[2:3]
	v_mov_b64_e32 v[94:95], v[2:3]
	v_mov_b64_e32 v[98:99], v[2:3]
	v_mov_b64_e32 v[110:111], v[2:3]
	v_mov_b64_e32 v[114:115], v[2:3]
	v_mov_b64_e32 v[146:147], v[2:3]
	v_mov_b64_e32 v[150:151], v[2:3]
	v_lshl_add_u64 v[116:117], s[56:57], 0, v[164:165]
	v_lshl_add_u64 v[118:119], s[56:57], 0, v[166:167]
	s_addc_u32 s84, s55, 0
	s_mov_b32 s85, -2
	s_mov_b64 s[54:55], 0
	v_add_u32_e32 v120, s14, v201
	v_mov_b64_e32 v[4:5], v[0:1]
	v_mov_b64_e32 v[8:9], v[0:1]
	v_mov_b64_e32 v[20:21], v[0:1]
	v_mov_b64_e32 v[24:25], v[0:1]
	v_mov_b64_e32 v[36:37], v[0:1]
	v_mov_b64_e32 v[40:41], v[0:1]
	v_mov_b64_e32 v[52:53], v[0:1]
	v_mov_b64_e32 v[56:57], v[0:1]
	v_mov_b64_e32 v[12:13], v[0:1]
	v_mov_b64_e32 v[16:17], v[0:1]
	v_mov_b64_e32 v[28:29], v[0:1]
	v_mov_b64_e32 v[32:33], v[0:1]
	v_mov_b64_e32 v[44:45], v[0:1]
	v_mov_b64_e32 v[48:49], v[0:1]
	v_mov_b64_e32 v[60:61], v[0:1]
	v_mov_b64_e32 v[64:65], v[0:1]
	v_mov_b64_e32 v[68:69], v[0:1]
	v_mov_b64_e32 v[72:73], v[0:1]
	v_mov_b64_e32 v[84:85], v[0:1]
	v_mov_b64_e32 v[88:89], v[0:1]
	v_mov_b64_e32 v[100:101], v[0:1]
	v_mov_b64_e32 v[104:105], v[0:1]
	v_mov_b64_e32 v[132:133], v[0:1]
	v_mov_b64_e32 v[136:137], v[0:1]
	v_mov_b64_e32 v[76:77], v[0:1]
	v_mov_b64_e32 v[80:81], v[0:1]
	v_mov_b64_e32 v[92:93], v[0:1]
	v_mov_b64_e32 v[96:97], v[0:1]
	v_mov_b64_e32 v[108:109], v[0:1]
	v_mov_b64_e32 v[112:113], v[0:1]
	v_mov_b64_e32 v[144:145], v[0:1]
	v_mov_b64_e32 v[148:149], v[0:1]
	s_branch .LBB0_864
	.p2align	6
